# layer 0 too: latent-row w_out tiles apply the gated residual in the epilogue (same row-sum exchange), post phase of layer 0 only reloads the new rows for the next pre-norm and handles context rows
# speedup vs baseline: 1.0121x; 1.0013x over previous
.Lgo_fz_epi:
	s_nop 7
	s_nop 7
	s_load_dwordx2 s[94:95], s[88:89], 0x168
	s_load_dwordx2 s[98:99], s[88:89], 0x170
	s_load_dwordx2 s[2:3], s[88:89], 0xc0
	v_and_b32_e32 v160, 15, v167
	v_bfe_u32 v161, v167, 4, 2
	v_bfe_u32 v162, v167, 6, 2
	v_lshrrev_b32_e32 v163, 8, v167
	v_lshlrev_b32_e32 v163, 6, v163
	v_lshl_add_u32 v163, v161, 2, v163
	v_lshl_add_u32 v164, v162, 5, v160
	v_readlane_b32 s32, v255, 0
	s_lshr_b32 s45, s36, 8
	s_lshl_b32 s48, s45, 3
	s_lshr_b32 s57, s34, 8
	s_add_u32 s48, s48, s57
	s_lshl_b32 s48, s48, 10
	s_lshr_b32 s57, s36, 12
	s_mul_i32 s0, s32, 5
	s_add_u32 s57, s57, s0
	s_mul_i32 s57, s57, 0x6000
	s_add_u32 s57, s57, 0x4000
	v_lshlrev_b32_e32 v237, 2, v164
	s_lshl_b32 vcc_lo, s34, 2
	v_add_u32_e32 v237, vcc_lo, v237
	v_add_u32_e32 v168, s36, v163
	v_lshlrev_b32_e32 v168, 13, v168
	v_add_u32_e32 v168, v168, v237
	v_add_u32_e32 v169, 0x2000, v168
	v_add_u32_e32 v170, 0x4000, v168
	v_add_u32_e32 v171, 0x6000, v168
	s_lshl_b32 s0, s45, 2
	s_add_u32 s0, s0, 0x204
	v_mov_b32_e32 v234, s0
	s_lshl_b32 s0, s45, 13
	v_lshl_add_u32 v235, v167, 2, s0
	s_lshl_b32 s45, s32, 3
	s_add_u32 s45, s45, 8
	s_load_dwordx2 s[36:37], s[88:89], 0xc8
	s_load_dwordx2 s[34:35], s[88:89], 0xf0
	s_load_dwordx2 s[0:1], s[88:89], 0x0
	v_mul_f32_e32 v194, v124, v124
	v_fmac_f32_e32 v194, v120, v120
	v_fmac_f32_e32 v194, v100, v100
	v_fmac_f32_e32 v194, v96, v96
	v_mul_f32_e32 v195, v125, v125
	v_fmac_f32_e32 v195, v121, v121
	v_fmac_f32_e32 v195, v101, v101
	v_fmac_f32_e32 v195, v97, v97
	v_mul_f32_e32 v196, v126, v126
	v_fmac_f32_e32 v196, v122, v122
	v_fmac_f32_e32 v196, v102, v102
	v_fmac_f32_e32 v196, v98, v98
	v_mul_f32_e32 v197, v127, v127
	v_fmac_f32_e32 v197, v123, v123
	v_fmac_f32_e32 v197, v103, v103
	v_fmac_f32_e32 v197, v99, v99
	v_mul_f32_e32 v198, v116, v116
	v_fmac_f32_e32 v198, v112, v112
	v_fmac_f32_e32 v198, v92, v92
	v_fmac_f32_e32 v198, v88, v88
	v_mul_f32_e32 v199, v117, v117
	v_fmac_f32_e32 v199, v113, v113
	v_fmac_f32_e32 v199, v93, v93
	v_fmac_f32_e32 v199, v89, v89
	v_mul_f32_e32 v200, v118, v118
	v_fmac_f32_e32 v200, v114, v114
	v_fmac_f32_e32 v200, v94, v94
	v_fmac_f32_e32 v200, v90, v90
	v_mul_f32_e32 v201, v119, v119
	v_fmac_f32_e32 v201, v115, v115
	v_fmac_f32_e32 v201, v95, v95
	v_fmac_f32_e32 v201, v91, v91
	v_mul_f32_e32 v202, v108, v108
	v_fmac_f32_e32 v202, v104, v104
	v_fmac_f32_e32 v202, v80, v80
	v_fmac_f32_e32 v202, v72, v72
	v_mul_f32_e32 v203, v109, v109
	v_fmac_f32_e32 v203, v105, v105
	v_fmac_f32_e32 v203, v81, v81
	v_fmac_f32_e32 v203, v73, v73
	v_mul_f32_e32 v204, v110, v110
	v_fmac_f32_e32 v204, v106, v106
	v_fmac_f32_e32 v204, v82, v82
	v_fmac_f32_e32 v204, v74, v74
	v_mul_f32_e32 v205, v111, v111
	v_fmac_f32_e32 v205, v107, v107
	v_fmac_f32_e32 v205, v83, v83
	v_fmac_f32_e32 v205, v75, v75
	v_mul_f32_e32 v206, v84, v84
	v_fmac_f32_e32 v206, v76, v76
	v_fmac_f32_e32 v206, v68, v68
	v_fmac_f32_e32 v206, v64, v64
	v_mul_f32_e32 v207, v85, v85
	v_fmac_f32_e32 v207, v77, v77
	v_fmac_f32_e32 v207, v69, v69
	v_fmac_f32_e32 v207, v65, v65
	v_mul_f32_e32 v208, v86, v86
	v_fmac_f32_e32 v208, v78, v78
	v_fmac_f32_e32 v208, v70, v70
	v_fmac_f32_e32 v208, v66, v66
	v_mul_f32_e32 v209, v87, v87
	v_fmac_f32_e32 v209, v79, v79
	v_fmac_f32_e32 v209, v71, v71
	v_fmac_f32_e32 v209, v67, v67
	v_mul_f32_e32 v210, v60, v60
	v_fmac_f32_e32 v210, v56, v56
	v_fmac_f32_e32 v210, v32, v32
	v_fmac_f32_e32 v210, v24, v24
	v_mul_f32_e32 v211, v61, v61
	v_fmac_f32_e32 v211, v57, v57
	v_fmac_f32_e32 v211, v33, v33
	v_fmac_f32_e32 v211, v25, v25
	v_mul_f32_e32 v212, v62, v62
	v_fmac_f32_e32 v212, v58, v58
	v_fmac_f32_e32 v212, v34, v34
	v_fmac_f32_e32 v212, v26, v26
	v_mul_f32_e32 v213, v63, v63
	v_fmac_f32_e32 v213, v59, v59
	v_fmac_f32_e32 v213, v35, v35
	v_fmac_f32_e32 v213, v27, v27
	v_mul_f32_e32 v214, v52, v52
	v_fmac_f32_e32 v214, v48, v48
	v_fmac_f32_e32 v214, v20, v20
	v_fmac_f32_e32 v214, v16, v16
	v_mul_f32_e32 v215, v53, v53
	v_fmac_f32_e32 v215, v49, v49
	v_fmac_f32_e32 v215, v21, v21
	v_fmac_f32_e32 v215, v17, v17
	v_mul_f32_e32 v216, v54, v54
	v_fmac_f32_e32 v216, v50, v50
	v_fmac_f32_e32 v216, v22, v22
	v_fmac_f32_e32 v216, v18, v18
	v_mul_f32_e32 v217, v55, v55
	v_fmac_f32_e32 v217, v51, v51
	v_fmac_f32_e32 v217, v23, v23
	v_fmac_f32_e32 v217, v19, v19
	v_mul_f32_e32 v218, v44, v44
	v_fmac_f32_e32 v218, v40, v40
	v_fmac_f32_e32 v218, v12, v12
	v_fmac_f32_e32 v218, v8, v8
	v_mul_f32_e32 v219, v45, v45
	v_fmac_f32_e32 v219, v41, v41
	v_fmac_f32_e32 v219, v13, v13
	v_fmac_f32_e32 v219, v9, v9
	v_mul_f32_e32 v220, v46, v46
	v_fmac_f32_e32 v220, v42, v42
	v_fmac_f32_e32 v220, v14, v14
	v_fmac_f32_e32 v220, v10, v10
	v_mul_f32_e32 v221, v47, v47
	v_fmac_f32_e32 v221, v43, v43
	v_fmac_f32_e32 v221, v15, v15
	v_fmac_f32_e32 v221, v11, v11
	v_mul_f32_e32 v222, v36, v36
	v_fmac_f32_e32 v222, v28, v28
	v_fmac_f32_e32 v222, v4, v4
	v_fmac_f32_e32 v222, v0, v0
	v_mul_f32_e32 v223, v37, v37
	v_fmac_f32_e32 v223, v29, v29
	v_fmac_f32_e32 v223, v5, v5
	v_fmac_f32_e32 v223, v1, v1
	v_mul_f32_e32 v224, v38, v38
	v_fmac_f32_e32 v224, v30, v30
	v_fmac_f32_e32 v224, v6, v6
	v_fmac_f32_e32 v224, v2, v2
	v_mul_f32_e32 v225, v39, v39
	v_fmac_f32_e32 v225, v31, v31
	v_fmac_f32_e32 v225, v7, v7
	v_fmac_f32_e32 v225, v3, v3
	s_nop 1
	v_add_f32_dpp v194, v194, v194 row_ror:8 row_mask:0xf bank_mask:0xf
	v_add_f32_dpp v195, v195, v195 row_ror:8 row_mask:0xf bank_mask:0xf
	v_add_f32_dpp v196, v196, v196 row_ror:8 row_mask:0xf bank_mask:0xf
	v_add_f32_dpp v197, v197, v197 row_ror:8 row_mask:0xf bank_mask:0xf
	v_add_f32_dpp v198, v198, v198 row_ror:8 row_mask:0xf bank_mask:0xf
	v_add_f32_dpp v199, v199, v199 row_ror:8 row_mask:0xf bank_mask:0xf
	v_add_f32_dpp v200, v200, v200 row_ror:8 row_mask:0xf bank_mask:0xf
	v_add_f32_dpp v201, v201, v201 row_ror:8 row_mask:0xf bank_mask:0xf
	v_add_f32_dpp v202, v202, v202 row_ror:8 row_mask:0xf bank_mask:0xf
	v_add_f32_dpp v203, v203, v203 row_ror:8 row_mask:0xf bank_mask:0xf
	v_add_f32_dpp v204, v204, v204 row_ror:8 row_mask:0xf bank_mask:0xf
	v_add_f32_dpp v205, v205, v205 row_ror:8 row_mask:0xf bank_mask:0xf
	v_add_f32_dpp v206, v206, v206 row_ror:8 row_mask:0xf bank_mask:0xf
	v_add_f32_dpp v207, v207, v207 row_ror:8 row_mask:0xf bank_mask:0xf
	v_add_f32_dpp v208, v208, v208 row_ror:8 row_mask:0xf bank_mask:0xf
	v_add_f32_dpp v209, v209, v209 row_ror:8 row_mask:0xf bank_mask:0xf
	v_add_f32_dpp v210, v210, v210 row_ror:8 row_mask:0xf bank_mask:0xf
	v_add_f32_dpp v211, v211, v211 row_ror:8 row_mask:0xf bank_mask:0xf
	v_add_f32_dpp v212, v212, v212 row_ror:8 row_mask:0xf bank_mask:0xf
	v_add_f32_dpp v213, v213, v213 row_ror:8 row_mask:0xf bank_mask:0xf
	v_add_f32_dpp v214, v214, v214 row_ror:8 row_mask:0xf bank_mask:0xf
	v_add_f32_dpp v215, v215, v215 row_ror:8 row_mask:0xf bank_mask:0xf
	v_add_f32_dpp v216, v216, v216 row_ror:8 row_mask:0xf bank_mask:0xf
	v_add_f32_dpp v217, v217, v217 row_ror:8 row_mask:0xf bank_mask:0xf
	v_add_f32_dpp v218, v218, v218 row_ror:8 row_mask:0xf bank_mask:0xf
	v_add_f32_dpp v219, v219, v219 row_ror:8 row_mask:0xf bank_mask:0xf
	v_add_f32_dpp v220, v220, v220 row_ror:8 row_mask:0xf bank_mask:0xf
	v_add_f32_dpp v221, v221, v221 row_ror:8 row_mask:0xf bank_mask:0xf
	v_add_f32_dpp v222, v222, v222 row_ror:8 row_mask:0xf bank_mask:0xf
	v_add_f32_dpp v223, v223, v223 row_ror:8 row_mask:0xf bank_mask:0xf
	v_add_f32_dpp v224, v224, v224 row_ror:8 row_mask:0xf bank_mask:0xf
	v_add_f32_dpp v225, v225, v225 row_ror:8 row_mask:0xf bank_mask:0xf
	s_nop 1
	v_add_f32_dpp v194, v194, v194 row_ror:4 row_mask:0xf bank_mask:0xf
	v_add_f32_dpp v195, v195, v195 row_ror:4 row_mask:0xf bank_mask:0xf
	v_add_f32_dpp v196, v196, v196 row_ror:4 row_mask:0xf bank_mask:0xf
	v_add_f32_dpp v197, v197, v197 row_ror:4 row_mask:0xf bank_mask:0xf
	v_add_f32_dpp v198, v198, v198 row_ror:4 row_mask:0xf bank_mask:0xf
	v_add_f32_dpp v199, v199, v199 row_ror:4 row_mask:0xf bank_mask:0xf
	v_add_f32_dpp v200, v200, v200 row_ror:4 row_mask:0xf bank_mask:0xf
	v_add_f32_dpp v201, v201, v201 row_ror:4 row_mask:0xf bank_mask:0xf
	v_add_f32_dpp v202, v202, v202 row_ror:4 row_mask:0xf bank_mask:0xf
	v_add_f32_dpp v203, v203, v203 row_ror:4 row_mask:0xf bank_mask:0xf
	v_add_f32_dpp v204, v204, v204 row_ror:4 row_mask:0xf bank_mask:0xf
	v_add_f32_dpp v205, v205, v205 row_ror:4 row_mask:0xf bank_mask:0xf
	v_add_f32_dpp v206, v206, v206 row_ror:4 row_mask:0xf bank_mask:0xf
	v_add_f32_dpp v207, v207, v207 row_ror:4 row_mask:0xf bank_mask:0xf
	v_add_f32_dpp v208, v208, v208 row_ror:4 row_mask:0xf bank_mask:0xf
	v_add_f32_dpp v209, v209, v209 row_ror:4 row_mask:0xf bank_mask:0xf
	v_add_f32_dpp v210, v210, v210 row_ror:4 row_mask:0xf bank_mask:0xf
	v_add_f32_dpp v211, v211, v211 row_ror:4 row_mask:0xf bank_mask:0xf
	v_add_f32_dpp v212, v212, v212 row_ror:4 row_mask:0xf bank_mask:0xf
	v_add_f32_dpp v213, v213, v213 row_ror:4 row_mask:0xf bank_mask:0xf
	v_add_f32_dpp v214, v214, v214 row_ror:4 row_mask:0xf bank_mask:0xf
	v_add_f32_dpp v215, v215, v215 row_ror:4 row_mask:0xf bank_mask:0xf
	v_add_f32_dpp v216, v216, v216 row_ror:4 row_mask:0xf bank_mask:0xf
	v_add_f32_dpp v217, v217, v217 row_ror:4 row_mask:0xf bank_mask:0xf
	v_add_f32_dpp v218, v218, v218 row_ror:4 row_mask:0xf bank_mask:0xf
	v_add_f32_dpp v219, v219, v219 row_ror:4 row_mask:0xf bank_mask:0xf
	v_add_f32_dpp v220, v220, v220 row_ror:4 row_mask:0xf bank_mask:0xf
	v_add_f32_dpp v221, v221, v221 row_ror:4 row_mask:0xf bank_mask:0xf
	v_add_f32_dpp v222, v222, v222 row_ror:4 row_mask:0xf bank_mask:0xf
	v_add_f32_dpp v223, v223, v223 row_ror:4 row_mask:0xf bank_mask:0xf
	v_add_f32_dpp v224, v224, v224 row_ror:4 row_mask:0xf bank_mask:0xf
	v_add_f32_dpp v225, v225, v225 row_ror:4 row_mask:0xf bank_mask:0xf
	s_nop 1
	v_add_f32_dpp v194, v194, v194 row_ror:2 row_mask:0xf bank_mask:0xf
	v_add_f32_dpp v195, v195, v195 row_ror:2 row_mask:0xf bank_mask:0xf
	v_add_f32_dpp v196, v196, v196 row_ror:2 row_mask:0xf bank_mask:0xf
	v_add_f32_dpp v197, v197, v197 row_ror:2 row_mask:0xf bank_mask:0xf
	v_add_f32_dpp v198, v198, v198 row_ror:2 row_mask:0xf bank_mask:0xf
	v_add_f32_dpp v199, v199, v199 row_ror:2 row_mask:0xf bank_mask:0xf
	v_add_f32_dpp v200, v200, v200 row_ror:2 row_mask:0xf bank_mask:0xf
	v_add_f32_dpp v201, v201, v201 row_ror:2 row_mask:0xf bank_mask:0xf
	v_add_f32_dpp v202, v202, v202 row_ror:2 row_mask:0xf bank_mask:0xf
	v_add_f32_dpp v203, v203, v203 row_ror:2 row_mask:0xf bank_mask:0xf
	v_add_f32_dpp v204, v204, v204 row_ror:2 row_mask:0xf bank_mask:0xf
	v_add_f32_dpp v205, v205, v205 row_ror:2 row_mask:0xf bank_mask:0xf
	v_add_f32_dpp v206, v206, v206 row_ror:2 row_mask:0xf bank_mask:0xf
	v_add_f32_dpp v207, v207, v207 row_ror:2 row_mask:0xf bank_mask:0xf
	v_add_f32_dpp v208, v208, v208 row_ror:2 row_mask:0xf bank_mask:0xf
	v_add_f32_dpp v209, v209, v209 row_ror:2 row_mask:0xf bank_mask:0xf
	v_add_f32_dpp v210, v210, v210 row_ror:2 row_mask:0xf bank_mask:0xf
	v_add_f32_dpp v211, v211, v211 row_ror:2 row_mask:0xf bank_mask:0xf
	v_add_f32_dpp v212, v212, v212 row_ror:2 row_mask:0xf bank_mask:0xf
	v_add_f32_dpp v213, v213, v213 row_ror:2 row_mask:0xf bank_mask:0xf
	v_add_f32_dpp v214, v214, v214 row_ror:2 row_mask:0xf bank_mask:0xf
	v_add_f32_dpp v215, v215, v215 row_ror:2 row_mask:0xf bank_mask:0xf
	v_add_f32_dpp v216, v216, v216 row_ror:2 row_mask:0xf bank_mask:0xf
	v_add_f32_dpp v217, v217, v217 row_ror:2 row_mask:0xf bank_mask:0xf
	v_add_f32_dpp v218, v218, v218 row_ror:2 row_mask:0xf bank_mask:0xf
	v_add_f32_dpp v219, v219, v219 row_ror:2 row_mask:0xf bank_mask:0xf
	v_add_f32_dpp v220, v220, v220 row_ror:2 row_mask:0xf bank_mask:0xf
	v_add_f32_dpp v221, v221, v221 row_ror:2 row_mask:0xf bank_mask:0xf
	v_add_f32_dpp v222, v222, v222 row_ror:2 row_mask:0xf bank_mask:0xf
	v_add_f32_dpp v223, v223, v223 row_ror:2 row_mask:0xf bank_mask:0xf
	v_add_f32_dpp v224, v224, v224 row_ror:2 row_mask:0xf bank_mask:0xf
	v_add_f32_dpp v225, v225, v225 row_ror:2 row_mask:0xf bank_mask:0xf
	s_nop 1
	v_add_f32_dpp v194, v194, v194 row_ror:1 row_mask:0xf bank_mask:0xf
	v_add_f32_dpp v195, v195, v195 row_ror:1 row_mask:0xf bank_mask:0xf
	v_add_f32_dpp v196, v196, v196 row_ror:1 row_mask:0xf bank_mask:0xf
	v_add_f32_dpp v197, v197, v197 row_ror:1 row_mask:0xf bank_mask:0xf
	v_add_f32_dpp v198, v198, v198 row_ror:1 row_mask:0xf bank_mask:0xf
	v_add_f32_dpp v199, v199, v199 row_ror:1 row_mask:0xf bank_mask:0xf
	v_add_f32_dpp v200, v200, v200 row_ror:1 row_mask:0xf bank_mask:0xf
	v_add_f32_dpp v201, v201, v201 row_ror:1 row_mask:0xf bank_mask:0xf
	v_add_f32_dpp v202, v202, v202 row_ror:1 row_mask:0xf bank_mask:0xf
	v_add_f32_dpp v203, v203, v203 row_ror:1 row_mask:0xf bank_mask:0xf
	v_add_f32_dpp v204, v204, v204 row_ror:1 row_mask:0xf bank_mask:0xf
	v_add_f32_dpp v205, v205, v205 row_ror:1 row_mask:0xf bank_mask:0xf
	v_add_f32_dpp v206, v206, v206 row_ror:1 row_mask:0xf bank_mask:0xf
	v_add_f32_dpp v207, v207, v207 row_ror:1 row_mask:0xf bank_mask:0xf
	v_add_f32_dpp v208, v208, v208 row_ror:1 row_mask:0xf bank_mask:0xf
	v_add_f32_dpp v209, v209, v209 row_ror:1 row_mask:0xf bank_mask:0xf
	v_add_f32_dpp v210, v210, v210 row_ror:1 row_mask:0xf bank_mask:0xf
	v_add_f32_dpp v211, v211, v211 row_ror:1 row_mask:0xf bank_mask:0xf
	v_add_f32_dpp v212, v212, v212 row_ror:1 row_mask:0xf bank_mask:0xf
	v_add_f32_dpp v213, v213, v213 row_ror:1 row_mask:0xf bank_mask:0xf
	v_add_f32_dpp v214, v214, v214 row_ror:1 row_mask:0xf bank_mask:0xf
	v_add_f32_dpp v215, v215, v215 row_ror:1 row_mask:0xf bank_mask:0xf
	v_add_f32_dpp v216, v216, v216 row_ror:1 row_mask:0xf bank_mask:0xf
	v_add_f32_dpp v217, v217, v217 row_ror:1 row_mask:0xf bank_mask:0xf
	v_add_f32_dpp v218, v218, v218 row_ror:1 row_mask:0xf bank_mask:0xf
	v_add_f32_dpp v219, v219, v219 row_ror:1 row_mask:0xf bank_mask:0xf
	v_add_f32_dpp v220, v220, v220 row_ror:1 row_mask:0xf bank_mask:0xf
	v_add_f32_dpp v221, v221, v221 row_ror:1 row_mask:0xf bank_mask:0xf
	v_add_f32_dpp v222, v222, v222 row_ror:1 row_mask:0xf bank_mask:0xf
	v_add_f32_dpp v223, v223, v223 row_ror:1 row_mask:0xf bank_mask:0xf
	v_add_f32_dpp v224, v224, v224 row_ror:1 row_mask:0xf bank_mask:0xf
	v_add_f32_dpp v225, v225, v225 row_ror:1 row_mask:0xf bank_mask:0xf
	v_lshlrev_b32_e32 v236, 10, v162
	v_lshl_add_u32 v236, v163, 2, v236
	v_add_u32_e32 v236, 0x20000, v236
	v_cmp_eq_u32_e32 vcc, 0, v160
	s_mov_b64 exec, vcc
	ds_write_b128 v236, v[194:197]
	ds_write_b128 v236, v[198:201] offset:64
	ds_write_b128 v236, v[202:205] offset:128
	ds_write_b128 v236, v[206:209] offset:192
	ds_write_b128 v236, v[210:213] offset:512
	ds_write_b128 v236, v[214:217] offset:576
	ds_write_b128 v236, v[218:221] offset:640
	ds_write_b128 v236, v[222:225] offset:704
	s_mov_b64 exec, -1
	s_waitcnt lgkmcnt(0)
	s_add_u32 s34, s34, s57
	s_addc_u32 s35, s35, 0
	s_lshl_b32 s57, s32, 13
	s_add_u32 s2, s2, s57
	s_addc_u32 s3, s3, 0
	s_cmp_eq_u32 s32, 0
	s_cselect_b32 s0, s0, s36
	s_cselect_b32 s1, s1, s37
	s_add_u32 s94, s94, 0x1000000
	s_addc_u32 s95, s95, 0
	v_readfirstlane_b32 s32, v167
	s_barrier
	s_cmp_lt_u32 s32, 0x100
	s_cbranch_scc0 .Lgo_fz_w1
	v_lshlrev_b32_e32 v238, 2, v167
	v_add_u32_e32 v239, 0x20000, v238
	ds_read_b32 v240, v239
	ds_read_b32 v241, v239 offset:1024
	ds_read_b32 v242, v239 offset:2048
	ds_read_b32 v243, v239 offset:3072
	v_add_u32_e32 v244, s48, v238
	s_waitcnt lgkmcnt(0)
	v_add_f32_e32 v240, v240, v241
	v_add_f32_e32 v240, v240, v242
	v_add_f32_e32 v240, v240, v243
	global_store_dword v244, v240, s[94:95] sc0 sc1
	s_waitcnt vmcnt(0)
.Lgo_fz_w1:
	s_cmp_lt_u32 s32, 64
	s_cbranch_scc1 .Lgo_fz_nopf
	global_load_dword v226, v237, s[34:35]
	global_load_dword v230, v237, s[2:3]
	global_load_dword v227, v237, s[34:35] offset:64
	global_load_dword v231, v237, s[2:3] offset:64
	global_load_dword v228, v237, s[34:35] offset:512
	global_load_dword v232, v237, s[2:3] offset:512
	global_load_dword v229, v237, s[34:35] offset:576
	global_load_dword v233, v237, s[2:3] offset:576
	v_mov_b32_e32 v172, v168
	v_mov_b32_e32 v173, v169
	v_mov_b32_e32 v174, v170
	v_mov_b32_e32 v175, v171
	global_load_dword v128, v172, s[0:1]
	global_load_dword v129, v173, s[0:1]
	global_load_dword v130, v174, s[0:1]
	global_load_dword v131, v175, s[0:1]
	global_load_dword v132, v172, s[0:1] offset:64
	global_load_dword v133, v173, s[0:1] offset:64
	global_load_dword v134, v174, s[0:1] offset:64
	global_load_dword v135, v175, s[0:1] offset:64
	global_load_dword v136, v172, s[0:1] offset:512
	global_load_dword v137, v173, s[0:1] offset:512
	global_load_dword v138, v174, s[0:1] offset:512
	global_load_dword v139, v175, s[0:1] offset:512
	global_load_dword v140, v172, s[0:1] offset:576
	global_load_dword v141, v173, s[0:1] offset:576
	global_load_dword v142, v174, s[0:1] offset:576
	global_load_dword v143, v175, s[0:1] offset:576
	v_add_u32_e32 v176, 0x20000, v168
	v_add_u32_e32 v177, 0x20000, v169
	v_add_u32_e32 v178, 0x20000, v170
	v_add_u32_e32 v179, 0x20000, v171
	global_load_dword v144, v176, s[0:1]
	global_load_dword v145, v177, s[0:1]
	global_load_dword v146, v178, s[0:1]
	global_load_dword v147, v179, s[0:1]
	global_load_dword v148, v176, s[0:1] offset:64
	global_load_dword v149, v177, s[0:1] offset:64
	global_load_dword v150, v178, s[0:1] offset:64
	global_load_dword v151, v179, s[0:1] offset:64
	global_load_dword v152, v176, s[0:1] offset:512
	global_load_dword v153, v177, s[0:1] offset:512
	global_load_dword v154, v178, s[0:1] offset:512
	global_load_dword v155, v179, s[0:1] offset:512
	global_load_dword v156, v176, s[0:1] offset:576
	global_load_dword v157, v177, s[0:1] offset:576
	global_load_dword v158, v178, s[0:1] offset:576
	global_load_dword v159, v179, s[0:1] offset:576
.Lgo_fz_nopf:
	s_barrier
	s_cmp_lt_u32 s32, 64
	s_cbranch_scc0 .Lgo_fz_w2
	v_mov_b32_e32 v245, v234
	v_mov_b32_e32 v246, 1
	s_mov_b64 exec, 1
	global_atomic_add v245, v246, s[98:99]
	s_mov_b32 s57, 0
.Lgo_fz_poll:
	global_load_dword v247, v245, s[98:99] sc1
	s_waitcnt vmcnt(0)
	v_readfirstlane_b32 vcc_lo, v247
	s_cmp_ge_u32 vcc_lo, s45
	s_cbranch_scc1 .Lgo_fz_got
	s_sleep 1
	s_add_u32 s57, s57, 1
	s_cmp_lt_u32 s57, 0x200000
	s_cbranch_scc1 .Lgo_fz_poll
.Lgo_fz_got:
	s_mov_b64 exec, -1
	buffer_inv sc1
	global_load_dword v226, v237, s[34:35]
	global_load_dword v230, v237, s[2:3]
	global_load_dword v227, v237, s[34:35] offset:64
	global_load_dword v231, v237, s[2:3] offset:64
	global_load_dword v228, v237, s[34:35] offset:512
	global_load_dword v232, v237, s[2:3] offset:512
	global_load_dword v229, v237, s[34:35] offset:576
	global_load_dword v233, v237, s[2:3] offset:576
	v_mov_b32_e32 v172, v168
	v_mov_b32_e32 v173, v169
	v_mov_b32_e32 v174, v170
	v_mov_b32_e32 v175, v171
	global_load_dword v128, v172, s[0:1]
	global_load_dword v129, v173, s[0:1]
	global_load_dword v130, v174, s[0:1]
	global_load_dword v131, v175, s[0:1]
	global_load_dword v132, v172, s[0:1] offset:64
	global_load_dword v133, v173, s[0:1] offset:64
	global_load_dword v134, v174, s[0:1] offset:64
	global_load_dword v135, v175, s[0:1] offset:64
	global_load_dword v136, v172, s[0:1] offset:512
	global_load_dword v137, v173, s[0:1] offset:512
	global_load_dword v138, v174, s[0:1] offset:512
	global_load_dword v139, v175, s[0:1] offset:512
	global_load_dword v140, v172, s[0:1] offset:576
	global_load_dword v141, v173, s[0:1] offset:576
	global_load_dword v142, v174, s[0:1] offset:576
	global_load_dword v143, v175, s[0:1] offset:576
	v_add_u32_e32 v176, 0x20000, v168
	v_add_u32_e32 v177, 0x20000, v169
	v_add_u32_e32 v178, 0x20000, v170
	v_add_u32_e32 v179, 0x20000, v171
	global_load_dword v144, v176, s[0:1]
	global_load_dword v145, v177, s[0:1]
	global_load_dword v146, v178, s[0:1]
	global_load_dword v147, v179, s[0:1]
	global_load_dword v148, v176, s[0:1] offset:64
	global_load_dword v149, v177, s[0:1] offset:64
	global_load_dword v150, v178, s[0:1] offset:64
	global_load_dword v151, v179, s[0:1] offset:64
	global_load_dword v152, v176, s[0:1] offset:512
	global_load_dword v153, v177, s[0:1] offset:512
	global_load_dword v154, v178, s[0:1] offset:512
	global_load_dword v155, v179, s[0:1] offset:512
	global_load_dword v156, v176, s[0:1] offset:576
	global_load_dword v157, v177, s[0:1] offset:576
	global_load_dword v158, v178, s[0:1] offset:576
	global_load_dword v159, v179, s[0:1] offset:576
.Lgo_fz_w2:
	s_barrier
	s_cmp_lt_u32 s32, 0x100
	s_cbranch_scc0 .Lgo_fz_w3
	v_mov_b32_e32 v244, v235
	v_add_u32_e32 v245, 0x1000, v244
	global_load_dword v246, v244, s[94:95] sc0 sc1
	global_load_dword v247, v244, s[94:95] offset:1024 sc0 sc1
	global_load_dword v248, v244, s[94:95] offset:2048 sc0 sc1
	global_load_dword v249, v244, s[94:95] offset:3072 sc0 sc1
	global_load_dword v250, v245, s[94:95] sc0 sc1
	global_load_dword v251, v245, s[94:95] offset:1024 sc0 sc1
	global_load_dword v252, v245, s[94:95] offset:2048 sc0 sc1
	global_load_dword v253, v245, s[94:95] offset:3072 sc0 sc1
	s_waitcnt vmcnt(0)
	v_add_f32_e32 v246, v246, v247
	v_add_f32_e32 v246, v246, v248
	v_add_f32_e32 v246, v246, v249
	v_add_f32_e32 v246, v246, v250
	v_add_f32_e32 v246, v246, v251
	v_add_f32_e32 v246, v246, v252
	v_add_f32_e32 v246, v246, v253
	v_fmamk_f32 v246, v246, 0x3a000000, v166
	v_mul_f32_e32 v247, 0x4b800000, v246
	v_cmp_gt_f32_e32 vcc, s58, v246
	s_nop 1
	v_cndmask_b32_e32 v246, v246, v247, vcc
	v_rsq_f32_e32 v248, v246
	s_nop 0
	v_mul_f32_e32 v247, 0x45800000, v248
	v_cndmask_b32_e32 v248, v248, v247, vcc
	ds_write_b32 v239, v248
	s_waitcnt lgkmcnt(0)
.Lgo_fz_w3:
	s_barrier
	v_lshlrev_b32_e32 v236, 2, v163
	v_add_u32_e32 v236, 0x20000, v236
	ds_read_b128 v[194:197], v236
	ds_read_b128 v[198:201], v236 offset:64
	ds_read_b128 v[202:205], v236 offset:128
	ds_read_b128 v[206:209], v236 offset:192
	ds_read_b128 v[210:213], v236 offset:512
	ds_read_b128 v[214:217], v236 offset:576
	ds_read_b128 v[218:221], v236 offset:640
	ds_read_b128 v[222:225], v236 offset:704
	s_waitcnt lgkmcnt(0)
	s_waitcnt vmcnt(16)
	v_mul_f32_e32 v124, v124, v226
	v_mul_f32_e32 v124, v124, v194
	v_fma_f32 v124, v124, v230, v128
	v_mul_f32_e32 v125, v125, v226
	v_mul_f32_e32 v125, v125, v195
	v_fma_f32 v125, v125, v230, v129
	v_mul_f32_e32 v126, v126, v226
	v_mul_f32_e32 v126, v126, v196
	v_fma_f32 v126, v126, v230, v130
	v_mul_f32_e32 v127, v127, v226
	v_mul_f32_e32 v127, v127, v197
	v_fma_f32 v127, v127, v230, v131
	v_mul_f32_e32 v120, v120, v227
	v_mul_f32_e32 v120, v120, v194
	v_fma_f32 v120, v120, v231, v132
	v_mul_f32_e32 v121, v121, v227
	v_mul_f32_e32 v121, v121, v195
	v_fma_f32 v121, v121, v231, v133
	v_mul_f32_e32 v122, v122, v227
	v_mul_f32_e32 v122, v122, v196
	v_fma_f32 v122, v122, v231, v134
	v_mul_f32_e32 v123, v123, v227
	v_mul_f32_e32 v123, v123, v197
	v_fma_f32 v123, v123, v231, v135
	v_mul_f32_e32 v100, v100, v228
	v_mul_f32_e32 v100, v100, v194
	v_fma_f32 v100, v100, v232, v136
	v_mul_f32_e32 v101, v101, v228
	v_mul_f32_e32 v101, v101, v195
	v_fma_f32 v101, v101, v232, v137
	v_mul_f32_e32 v102, v102, v228
	v_mul_f32_e32 v102, v102, v196
	v_fma_f32 v102, v102, v232, v138
	v_mul_f32_e32 v103, v103, v228
	v_mul_f32_e32 v103, v103, v197
	v_fma_f32 v103, v103, v232, v139
	v_mul_f32_e32 v96, v96, v229
	v_mul_f32_e32 v96, v96, v194
	v_fma_f32 v96, v96, v233, v140
	v_mul_f32_e32 v97, v97, v229
	v_mul_f32_e32 v97, v97, v195
	v_fma_f32 v97, v97, v233, v141
	v_mul_f32_e32 v98, v98, v229
	v_mul_f32_e32 v98, v98, v196
	v_fma_f32 v98, v98, v233, v142
	v_mul_f32_e32 v99, v99, v229
	v_mul_f32_e32 v99, v99, v197
	v_fma_f32 v99, v99, v233, v143
	global_store_dword v172, v124, s[36:37]
	global_store_dword v173, v125, s[36:37]
	global_store_dword v174, v126, s[36:37]
	global_store_dword v175, v127, s[36:37]
	global_store_dword v172, v120, s[36:37] offset:64
	global_store_dword v173, v121, s[36:37] offset:64
	global_store_dword v174, v122, s[36:37] offset:64
	global_store_dword v175, v123, s[36:37] offset:64
	global_store_dword v172, v100, s[36:37] offset:512
	global_store_dword v173, v101, s[36:37] offset:512
	global_store_dword v174, v102, s[36:37] offset:512
	global_store_dword v175, v103, s[36:37] offset:512
	global_store_dword v172, v96, s[36:37] offset:576
	global_store_dword v173, v97, s[36:37] offset:576
	global_store_dword v174, v98, s[36:37] offset:576
	global_store_dword v175, v99, s[36:37] offset:576
	v_add_u32_e32 v172, 0x40000, v168
	v_add_u32_e32 v173, 0x40000, v169
	v_add_u32_e32 v174, 0x40000, v170
	v_add_u32_e32 v175, 0x40000, v171
	global_load_dword v128, v172, s[0:1]
	global_load_dword v129, v173, s[0:1]
	global_load_dword v130, v174, s[0:1]
	global_load_dword v131, v175, s[0:1]
	global_load_dword v132, v172, s[0:1] offset:64
	global_load_dword v133, v173, s[0:1] offset:64
	global_load_dword v134, v174, s[0:1] offset:64
	global_load_dword v135, v175, s[0:1] offset:64
	global_load_dword v136, v172, s[0:1] offset:512
	global_load_dword v137, v173, s[0:1] offset:512
	global_load_dword v138, v174, s[0:1] offset:512
	global_load_dword v139, v175, s[0:1] offset:512
	global_load_dword v140, v172, s[0:1] offset:576
	global_load_dword v141, v173, s[0:1] offset:576
	global_load_dword v142, v174, s[0:1] offset:576
	global_load_dword v143, v175, s[0:1] offset:576
	s_waitcnt vmcnt(32)
	v_mul_f32_e32 v116, v116, v226
	v_mul_f32_e32 v116, v116, v198
	v_fma_f32 v116, v116, v230, v144
	v_mul_f32_e32 v117, v117, v226
	v_mul_f32_e32 v117, v117, v199
	v_fma_f32 v117, v117, v230, v145
	v_mul_f32_e32 v118, v118, v226
	v_mul_f32_e32 v118, v118, v200
	v_fma_f32 v118, v118, v230, v146
	v_mul_f32_e32 v119, v119, v226
	v_mul_f32_e32 v119, v119, v201
	v_fma_f32 v119, v119, v230, v147
	v_mul_f32_e32 v112, v112, v227
	v_mul_f32_e32 v112, v112, v198
	v_fma_f32 v112, v112, v231, v148
	v_mul_f32_e32 v113, v113, v227
	v_mul_f32_e32 v113, v113, v199
	v_fma_f32 v113, v113, v231, v149
	v_mul_f32_e32 v114, v114, v227
	v_mul_f32_e32 v114, v114, v200
	v_fma_f32 v114, v114, v231, v150
	v_mul_f32_e32 v115, v115, v227
	v_mul_f32_e32 v115, v115, v201
	v_fma_f32 v115, v115, v231, v151
	v_mul_f32_e32 v92, v92, v228
	v_mul_f32_e32 v92, v92, v198
	v_fma_f32 v92, v92, v232, v152
	v_mul_f32_e32 v93, v93, v228
	v_mul_f32_e32 v93, v93, v199
	v_fma_f32 v93, v93, v232, v153
	v_mul_f32_e32 v94, v94, v228
	v_mul_f32_e32 v94, v94, v200
	v_fma_f32 v94, v94, v232, v154
	v_mul_f32_e32 v95, v95, v228
	v_mul_f32_e32 v95, v95, v201
	v_fma_f32 v95, v95, v232, v155
	v_mul_f32_e32 v88, v88, v229
	v_mul_f32_e32 v88, v88, v198
	v_fma_f32 v88, v88, v233, v156
	v_mul_f32_e32 v89, v89, v229
	v_mul_f32_e32 v89, v89, v199
	v_fma_f32 v89, v89, v233, v157
	v_mul_f32_e32 v90, v90, v229
	v_mul_f32_e32 v90, v90, v200
	v_fma_f32 v90, v90, v233, v158
	v_mul_f32_e32 v91, v91, v229
	v_mul_f32_e32 v91, v91, v201
	v_fma_f32 v91, v91, v233, v159
	global_store_dword v176, v116, s[36:37]
	global_store_dword v177, v117, s[36:37]
	global_store_dword v178, v118, s[36:37]
	global_store_dword v179, v119, s[36:37]
	global_store_dword v176, v112, s[36:37] offset:64
	global_store_dword v177, v113, s[36:37] offset:64
	global_store_dword v178, v114, s[36:37] offset:64
	global_store_dword v179, v115, s[36:37] offset:64
	global_store_dword v176, v92, s[36:37] offset:512
	global_store_dword v177, v93, s[36:37] offset:512
	global_store_dword v178, v94, s[36:37] offset:512
	global_store_dword v179, v95, s[36:37] offset:512
	global_store_dword v176, v88, s[36:37] offset:576
	global_store_dword v177, v89, s[36:37] offset:576
	global_store_dword v178, v90, s[36:37] offset:576
	global_store_dword v179, v91, s[36:37] offset:576
	v_add_u32_e32 v176, 0x60000, v168
	v_add_u32_e32 v177, 0x60000, v169
	v_add_u32_e32 v178, 0x60000, v170
	v_add_u32_e32 v179, 0x60000, v171
	global_load_dword v144, v176, s[0:1]
	global_load_dword v145, v177, s[0:1]
	global_load_dword v146, v178, s[0:1]
	global_load_dword v147, v179, s[0:1]
	global_load_dword v148, v176, s[0:1] offset:64
	global_load_dword v149, v177, s[0:1] offset:64
	global_load_dword v150, v178, s[0:1] offset:64
	global_load_dword v151, v179, s[0:1] offset:64
	global_load_dword v152, v176, s[0:1] offset:512
	global_load_dword v153, v177, s[0:1] offset:512
	global_load_dword v154, v178, s[0:1] offset:512
	global_load_dword v155, v179, s[0:1] offset:512
	global_load_dword v156, v176, s[0:1] offset:576
	global_load_dword v157, v177, s[0:1] offset:576
	global_load_dword v158, v178, s[0:1] offset:576
	global_load_dword v159, v179, s[0:1] offset:576
	s_waitcnt vmcnt(32)
	v_mul_f32_e32 v108, v108, v226
	v_mul_f32_e32 v108, v108, v202
	v_fma_f32 v108, v108, v230, v128
	v_mul_f32_e32 v109, v109, v226
	v_mul_f32_e32 v109, v109, v203
	v_fma_f32 v109, v109, v230, v129
	v_mul_f32_e32 v110, v110, v226
	v_mul_f32_e32 v110, v110, v204
	v_fma_f32 v110, v110, v230, v130
	v_mul_f32_e32 v111, v111, v226
	v_mul_f32_e32 v111, v111, v205
	v_fma_f32 v111, v111, v230, v131
	v_mul_f32_e32 v104, v104, v227
	v_mul_f32_e32 v104, v104, v202
	v_fma_f32 v104, v104, v231, v132
	v_mul_f32_e32 v105, v105, v227
	v_mul_f32_e32 v105, v105, v203
	v_fma_f32 v105, v105, v231, v133
	v_mul_f32_e32 v106, v106, v227
	v_mul_f32_e32 v106, v106, v204
	v_fma_f32 v106, v106, v231, v134
	v_mul_f32_e32 v107, v107, v227
	v_mul_f32_e32 v107, v107, v205
	v_fma_f32 v107, v107, v231, v135
	v_mul_f32_e32 v80, v80, v228
	v_mul_f32_e32 v80, v80, v202
	v_fma_f32 v80, v80, v232, v136
	v_mul_f32_e32 v81, v81, v228
	v_mul_f32_e32 v81, v81, v203
	v_fma_f32 v81, v81, v232, v137
	v_mul_f32_e32 v82, v82, v228
	v_mul_f32_e32 v82, v82, v204
	v_fma_f32 v82, v82, v232, v138
	v_mul_f32_e32 v83, v83, v228
	v_mul_f32_e32 v83, v83, v205
	v_fma_f32 v83, v83, v232, v139
	v_mul_f32_e32 v72, v72, v229
	v_mul_f32_e32 v72, v72, v202
	v_fma_f32 v72, v72, v233, v140
	v_mul_f32_e32 v73, v73, v229
	v_mul_f32_e32 v73, v73, v203
	v_fma_f32 v73, v73, v233, v141
	v_mul_f32_e32 v74, v74, v229
	v_mul_f32_e32 v74, v74, v204
	v_fma_f32 v74, v74, v233, v142
	v_mul_f32_e32 v75, v75, v229
	v_mul_f32_e32 v75, v75, v205
	v_fma_f32 v75, v75, v233, v143
	global_store_dword v172, v108, s[36:37]
	global_store_dword v173, v109, s[36:37]
	global_store_dword v174, v110, s[36:37]
	global_store_dword v175, v111, s[36:37]
	global_store_dword v172, v104, s[36:37] offset:64
	global_store_dword v173, v105, s[36:37] offset:64
	global_store_dword v174, v106, s[36:37] offset:64
	global_store_dword v175, v107, s[36:37] offset:64
	global_store_dword v172, v80, s[36:37] offset:512
	global_store_dword v173, v81, s[36:37] offset:512
	global_store_dword v174, v82, s[36:37] offset:512
	global_store_dword v175, v83, s[36:37] offset:512
	global_store_dword v172, v72, s[36:37] offset:576
	global_store_dword v173, v73, s[36:37] offset:576
	global_store_dword v174, v74, s[36:37] offset:576
	global_store_dword v175, v75, s[36:37] offset:576
	v_add_u32_e32 v172, 0x100000, v168
	v_add_u32_e32 v173, 0x100000, v169
	v_add_u32_e32 v174, 0x100000, v170
	v_add_u32_e32 v175, 0x100000, v171
	global_load_dword v128, v172, s[0:1]
	global_load_dword v129, v173, s[0:1]
	global_load_dword v130, v174, s[0:1]
	global_load_dword v131, v175, s[0:1]
	global_load_dword v132, v172, s[0:1] offset:64
	global_load_dword v133, v173, s[0:1] offset:64
	global_load_dword v134, v174, s[0:1] offset:64
	global_load_dword v135, v175, s[0:1] offset:64
	global_load_dword v136, v172, s[0:1] offset:512
	global_load_dword v137, v173, s[0:1] offset:512
	global_load_dword v138, v174, s[0:1] offset:512
	global_load_dword v139, v175, s[0:1] offset:512
	global_load_dword v140, v172, s[0:1] offset:576
	global_load_dword v141, v173, s[0:1] offset:576
	global_load_dword v142, v174, s[0:1] offset:576
	global_load_dword v143, v175, s[0:1] offset:576
	s_waitcnt vmcnt(32)
	v_mul_f32_e32 v84, v84, v226
	v_mul_f32_e32 v84, v84, v206
	v_fma_f32 v84, v84, v230, v144
	v_mul_f32_e32 v85, v85, v226
	v_mul_f32_e32 v85, v85, v207
	v_fma_f32 v85, v85, v230, v145
	v_mul_f32_e32 v86, v86, v226
	v_mul_f32_e32 v86, v86, v208
	v_fma_f32 v86, v86, v230, v146
	v_mul_f32_e32 v87, v87, v226
	v_mul_f32_e32 v87, v87, v209
	v_fma_f32 v87, v87, v230, v147
	v_mul_f32_e32 v76, v76, v227
	v_mul_f32_e32 v76, v76, v206
	v_fma_f32 v76, v76, v231, v148
	v_mul_f32_e32 v77, v77, v227
	v_mul_f32_e32 v77, v77, v207
	v_fma_f32 v77, v77, v231, v149
	v_mul_f32_e32 v78, v78, v227
	v_mul_f32_e32 v78, v78, v208
	v_fma_f32 v78, v78, v231, v150
	v_mul_f32_e32 v79, v79, v227
	v_mul_f32_e32 v79, v79, v209
	v_fma_f32 v79, v79, v231, v151
	v_mul_f32_e32 v68, v68, v228
	v_mul_f32_e32 v68, v68, v206
	v_fma_f32 v68, v68, v232, v152
	v_mul_f32_e32 v69, v69, v228
	v_mul_f32_e32 v69, v69, v207
	v_fma_f32 v69, v69, v232, v153
	v_mul_f32_e32 v70, v70, v228
	v_mul_f32_e32 v70, v70, v208
	v_fma_f32 v70, v70, v232, v154
	v_mul_f32_e32 v71, v71, v228
	v_mul_f32_e32 v71, v71, v209
	v_fma_f32 v71, v71, v232, v155
	v_mul_f32_e32 v64, v64, v229
	v_mul_f32_e32 v64, v64, v206
	v_fma_f32 v64, v64, v233, v156
	v_mul_f32_e32 v65, v65, v229
	v_mul_f32_e32 v65, v65, v207
	v_fma_f32 v65, v65, v233, v157
	v_mul_f32_e32 v66, v66, v229
	v_mul_f32_e32 v66, v66, v208
	v_fma_f32 v66, v66, v233, v158
	v_mul_f32_e32 v67, v67, v229
	v_mul_f32_e32 v67, v67, v209
	v_fma_f32 v67, v67, v233, v159
	global_store_dword v176, v84, s[36:37]
	global_store_dword v177, v85, s[36:37]
	global_store_dword v178, v86, s[36:37]
	global_store_dword v179, v87, s[36:37]
	global_store_dword v176, v76, s[36:37] offset:64
	global_store_dword v177, v77, s[36:37] offset:64
	global_store_dword v178, v78, s[36:37] offset:64
	global_store_dword v179, v79, s[36:37] offset:64
	global_store_dword v176, v68, s[36:37] offset:512
	global_store_dword v177, v69, s[36:37] offset:512
	global_store_dword v178, v70, s[36:37] offset:512
	global_store_dword v179, v71, s[36:37] offset:512
	global_store_dword v176, v64, s[36:37] offset:576
	global_store_dword v177, v65, s[36:37] offset:576
	global_store_dword v178, v66, s[36:37] offset:576
	global_store_dword v179, v67, s[36:37] offset:576
	v_add_u32_e32 v176, 0x120000, v168
	v_add_u32_e32 v177, 0x120000, v169
	v_add_u32_e32 v178, 0x120000, v170
	v_add_u32_e32 v179, 0x120000, v171
	global_load_dword v144, v176, s[0:1]
	global_load_dword v145, v177, s[0:1]
	global_load_dword v146, v178, s[0:1]
	global_load_dword v147, v179, s[0:1]
	global_load_dword v148, v176, s[0:1] offset:64
	global_load_dword v149, v177, s[0:1] offset:64
	global_load_dword v150, v178, s[0:1] offset:64
	global_load_dword v151, v179, s[0:1] offset:64
	global_load_dword v152, v176, s[0:1] offset:512
	global_load_dword v153, v177, s[0:1] offset:512
	global_load_dword v154, v178, s[0:1] offset:512
	global_load_dword v155, v179, s[0:1] offset:512
	global_load_dword v156, v176, s[0:1] offset:576
	global_load_dword v157, v177, s[0:1] offset:576
	global_load_dword v158, v178, s[0:1] offset:576
	global_load_dword v159, v179, s[0:1] offset:576
	s_waitcnt vmcnt(32)
	v_mul_f32_e32 v60, v60, v226
	v_mul_f32_e32 v60, v60, v210
	v_fma_f32 v60, v60, v230, v128
	v_mul_f32_e32 v61, v61, v226
	v_mul_f32_e32 v61, v61, v211
	v_fma_f32 v61, v61, v230, v129
	v_mul_f32_e32 v62, v62, v226
	v_mul_f32_e32 v62, v62, v212
	v_fma_f32 v62, v62, v230, v130
	v_mul_f32_e32 v63, v63, v226
	v_mul_f32_e32 v63, v63, v213
	v_fma_f32 v63, v63, v230, v131
	v_mul_f32_e32 v56, v56, v227
	v_mul_f32_e32 v56, v56, v210
	v_fma_f32 v56, v56, v231, v132
	v_mul_f32_e32 v57, v57, v227
	v_mul_f32_e32 v57, v57, v211
	v_fma_f32 v57, v57, v231, v133
	v_mul_f32_e32 v58, v58, v227
	v_mul_f32_e32 v58, v58, v212
	v_fma_f32 v58, v58, v231, v134
	v_mul_f32_e32 v59, v59, v227
	v_mul_f32_e32 v59, v59, v213
	v_fma_f32 v59, v59, v231, v135
	v_mul_f32_e32 v32, v32, v228
	v_mul_f32_e32 v32, v32, v210
	v_fma_f32 v32, v32, v232, v136
	v_mul_f32_e32 v33, v33, v228
	v_mul_f32_e32 v33, v33, v211
	v_fma_f32 v33, v33, v232, v137
	v_mul_f32_e32 v34, v34, v228
	v_mul_f32_e32 v34, v34, v212
	v_fma_f32 v34, v34, v232, v138
	v_mul_f32_e32 v35, v35, v228
	v_mul_f32_e32 v35, v35, v213
	v_fma_f32 v35, v35, v232, v139
	v_mul_f32_e32 v24, v24, v229
	v_mul_f32_e32 v24, v24, v210
	v_fma_f32 v24, v24, v233, v140
	v_mul_f32_e32 v25, v25, v229
	v_mul_f32_e32 v25, v25, v211
	v_fma_f32 v25, v25, v233, v141
	v_mul_f32_e32 v26, v26, v229
	v_mul_f32_e32 v26, v26, v212
	v_fma_f32 v26, v26, v233, v142
	v_mul_f32_e32 v27, v27, v229
	v_mul_f32_e32 v27, v27, v213
	v_fma_f32 v27, v27, v233, v143
	global_store_dword v172, v60, s[36:37]
	global_store_dword v173, v61, s[36:37]
	global_store_dword v174, v62, s[36:37]
	global_store_dword v175, v63, s[36:37]
	global_store_dword v172, v56, s[36:37] offset:64
	global_store_dword v173, v57, s[36:37] offset:64
	global_store_dword v174, v58, s[36:37] offset:64
	global_store_dword v175, v59, s[36:37] offset:64
	global_store_dword v172, v32, s[36:37] offset:512
	global_store_dword v173, v33, s[36:37] offset:512
	global_store_dword v174, v34, s[36:37] offset:512
	global_store_dword v175, v35, s[36:37] offset:512
	global_store_dword v172, v24, s[36:37] offset:576
	global_store_dword v173, v25, s[36:37] offset:576
	global_store_dword v174, v26, s[36:37] offset:576
	global_store_dword v175, v27, s[36:37] offset:576
	v_add_u32_e32 v172, 0x140000, v168
	v_add_u32_e32 v173, 0x140000, v169
	v_add_u32_e32 v174, 0x140000, v170
	v_add_u32_e32 v175, 0x140000, v171
	global_load_dword v128, v172, s[0:1]
	global_load_dword v129, v173, s[0:1]
	global_load_dword v130, v174, s[0:1]
	global_load_dword v131, v175, s[0:1]
	global_load_dword v132, v172, s[0:1] offset:64
	global_load_dword v133, v173, s[0:1] offset:64
	global_load_dword v134, v174, s[0:1] offset:64
	global_load_dword v135, v175, s[0:1] offset:64
	global_load_dword v136, v172, s[0:1] offset:512
	global_load_dword v137, v173, s[0:1] offset:512
	global_load_dword v138, v174, s[0:1] offset:512
	global_load_dword v139, v175, s[0:1] offset:512
	global_load_dword v140, v172, s[0:1] offset:576
	global_load_dword v141, v173, s[0:1] offset:576
	global_load_dword v142, v174, s[0:1] offset:576
	global_load_dword v143, v175, s[0:1] offset:576
	s_waitcnt vmcnt(32)
	v_mul_f32_e32 v52, v52, v226
	v_mul_f32_e32 v52, v52, v214
	v_fma_f32 v52, v52, v230, v144
	v_mul_f32_e32 v53, v53, v226
	v_mul_f32_e32 v53, v53, v215
	v_fma_f32 v53, v53, v230, v145
	v_mul_f32_e32 v54, v54, v226
	v_mul_f32_e32 v54, v54, v216
	v_fma_f32 v54, v54, v230, v146
	v_mul_f32_e32 v55, v55, v226
	v_mul_f32_e32 v55, v55, v217
	v_fma_f32 v55, v55, v230, v147
	v_mul_f32_e32 v48, v48, v227
	v_mul_f32_e32 v48, v48, v214
	v_fma_f32 v48, v48, v231, v148
	v_mul_f32_e32 v49, v49, v227
	v_mul_f32_e32 v49, v49, v215
	v_fma_f32 v49, v49, v231, v149
	v_mul_f32_e32 v50, v50, v227
	v_mul_f32_e32 v50, v50, v216
	v_fma_f32 v50, v50, v231, v150
	v_mul_f32_e32 v51, v51, v227
	v_mul_f32_e32 v51, v51, v217
	v_fma_f32 v51, v51, v231, v151
	v_mul_f32_e32 v20, v20, v228
	v_mul_f32_e32 v20, v20, v214
	v_fma_f32 v20, v20, v232, v152
	v_mul_f32_e32 v21, v21, v228
	v_mul_f32_e32 v21, v21, v215
	v_fma_f32 v21, v21, v232, v153
	v_mul_f32_e32 v22, v22, v228
	v_mul_f32_e32 v22, v22, v216
	v_fma_f32 v22, v22, v232, v154
	v_mul_f32_e32 v23, v23, v228
	v_mul_f32_e32 v23, v23, v217
	v_fma_f32 v23, v23, v232, v155
	v_mul_f32_e32 v16, v16, v229
	v_mul_f32_e32 v16, v16, v214
	v_fma_f32 v16, v16, v233, v156
	v_mul_f32_e32 v17, v17, v229
	v_mul_f32_e32 v17, v17, v215
	v_fma_f32 v17, v17, v233, v157
	v_mul_f32_e32 v18, v18, v229
	v_mul_f32_e32 v18, v18, v216
	v_fma_f32 v18, v18, v233, v158
	v_mul_f32_e32 v19, v19, v229
	v_mul_f32_e32 v19, v19, v217
	v_fma_f32 v19, v19, v233, v159
	global_store_dword v176, v52, s[36:37]
	global_store_dword v177, v53, s[36:37]
	global_store_dword v178, v54, s[36:37]
	global_store_dword v179, v55, s[36:37]
	global_store_dword v176, v48, s[36:37] offset:64
	global_store_dword v177, v49, s[36:37] offset:64
	global_store_dword v178, v50, s[36:37] offset:64
	global_store_dword v179, v51, s[36:37] offset:64
	global_store_dword v176, v20, s[36:37] offset:512
	global_store_dword v177, v21, s[36:37] offset:512
	global_store_dword v178, v22, s[36:37] offset:512
	global_store_dword v179, v23, s[36:37] offset:512
	global_store_dword v176, v16, s[36:37] offset:576
	global_store_dword v177, v17, s[36:37] offset:576
	global_store_dword v178, v18, s[36:37] offset:576
	global_store_dword v179, v19, s[36:37] offset:576
	v_add_u32_e32 v176, 0x160000, v168
	v_add_u32_e32 v177, 0x160000, v169
	v_add_u32_e32 v178, 0x160000, v170
	v_add_u32_e32 v179, 0x160000, v171
	global_load_dword v144, v176, s[0:1]
	global_load_dword v145, v177, s[0:1]
	global_load_dword v146, v178, s[0:1]
	global_load_dword v147, v179, s[0:1]
	global_load_dword v148, v176, s[0:1] offset:64
	global_load_dword v149, v177, s[0:1] offset:64
	global_load_dword v150, v178, s[0:1] offset:64
	global_load_dword v151, v179, s[0:1] offset:64
	global_load_dword v152, v176, s[0:1] offset:512
	global_load_dword v153, v177, s[0:1] offset:512
	global_load_dword v154, v178, s[0:1] offset:512
	global_load_dword v155, v179, s[0:1] offset:512
	global_load_dword v156, v176, s[0:1] offset:576
	global_load_dword v157, v177, s[0:1] offset:576
	global_load_dword v158, v178, s[0:1] offset:576
	global_load_dword v159, v179, s[0:1] offset:576
	s_waitcnt vmcnt(32)
	v_mul_f32_e32 v44, v44, v226
	v_mul_f32_e32 v44, v44, v218
	v_fma_f32 v44, v44, v230, v128
	v_mul_f32_e32 v45, v45, v226
	v_mul_f32_e32 v45, v45, v219
	v_fma_f32 v45, v45, v230, v129
	v_mul_f32_e32 v46, v46, v226
	v_mul_f32_e32 v46, v46, v220
	v_fma_f32 v46, v46, v230, v130
	v_mul_f32_e32 v47, v47, v226
	v_mul_f32_e32 v47, v47, v221
	v_fma_f32 v47, v47, v230, v131
	v_mul_f32_e32 v40, v40, v227
	v_mul_f32_e32 v40, v40, v218
	v_fma_f32 v40, v40, v231, v132
	v_mul_f32_e32 v41, v41, v227
	v_mul_f32_e32 v41, v41, v219
	v_fma_f32 v41, v41, v231, v133
	v_mul_f32_e32 v42, v42, v227
	v_mul_f32_e32 v42, v42, v220
	v_fma_f32 v42, v42, v231, v134
	v_mul_f32_e32 v43, v43, v227
	v_mul_f32_e32 v43, v43, v221
	v_fma_f32 v43, v43, v231, v135
	v_mul_f32_e32 v12, v12, v228
	v_mul_f32_e32 v12, v12, v218
	v_fma_f32 v12, v12, v232, v136
	v_mul_f32_e32 v13, v13, v228
	v_mul_f32_e32 v13, v13, v219
	v_fma_f32 v13, v13, v232, v137
	v_mul_f32_e32 v14, v14, v228
	v_mul_f32_e32 v14, v14, v220
	v_fma_f32 v14, v14, v232, v138
	v_mul_f32_e32 v15, v15, v228
	v_mul_f32_e32 v15, v15, v221
	v_fma_f32 v15, v15, v232, v139
	v_mul_f32_e32 v8, v8, v229
	v_mul_f32_e32 v8, v8, v218
	v_fma_f32 v8, v8, v233, v140
	v_mul_f32_e32 v9, v9, v229
	v_mul_f32_e32 v9, v9, v219
	v_fma_f32 v9, v9, v233, v141
	v_mul_f32_e32 v10, v10, v229
	v_mul_f32_e32 v10, v10, v220
	v_fma_f32 v10, v10, v233, v142
	v_mul_f32_e32 v11, v11, v229
	v_mul_f32_e32 v11, v11, v221
	v_fma_f32 v11, v11, v233, v143
	global_store_dword v172, v44, s[36:37]
	global_store_dword v173, v45, s[36:37]
	global_store_dword v174, v46, s[36:37]
	global_store_dword v175, v47, s[36:37]
	global_store_dword v172, v40, s[36:37] offset:64
	global_store_dword v173, v41, s[36:37] offset:64
	global_store_dword v174, v42, s[36:37] offset:64
	global_store_dword v175, v43, s[36:37] offset:64
	global_store_dword v172, v12, s[36:37] offset:512
	global_store_dword v173, v13, s[36:37] offset:512
	global_store_dword v174, v14, s[36:37] offset:512
	global_store_dword v175, v15, s[36:37] offset:512
	global_store_dword v172, v8, s[36:37] offset:576
	global_store_dword v173, v9, s[36:37] offset:576
	global_store_dword v174, v10, s[36:37] offset:576
	global_store_dword v175, v11, s[36:37] offset:576
	s_waitcnt vmcnt(16)
	v_mul_f32_e32 v36, v36, v226
	v_mul_f32_e32 v36, v36, v222
	v_fma_f32 v36, v36, v230, v144
	v_mul_f32_e32 v37, v37, v226
	v_mul_f32_e32 v37, v37, v223
	v_fma_f32 v37, v37, v230, v145
	v_mul_f32_e32 v38, v38, v226
	v_mul_f32_e32 v38, v38, v224
	v_fma_f32 v38, v38, v230, v146
	v_mul_f32_e32 v39, v39, v226
	v_mul_f32_e32 v39, v39, v225
	v_fma_f32 v39, v39, v230, v147
	v_mul_f32_e32 v28, v28, v227
	v_mul_f32_e32 v28, v28, v222
	v_fma_f32 v28, v28, v231, v148
	v_mul_f32_e32 v29, v29, v227
	v_mul_f32_e32 v29, v29, v223
	v_fma_f32 v29, v29, v231, v149
	v_mul_f32_e32 v30, v30, v227
	v_mul_f32_e32 v30, v30, v224
	v_fma_f32 v30, v30, v231, v150
	v_mul_f32_e32 v31, v31, v227
	v_mul_f32_e32 v31, v31, v225
	v_fma_f32 v31, v31, v231, v151
	v_mul_f32_e32 v4, v4, v228
	v_mul_f32_e32 v4, v4, v222
	v_fma_f32 v4, v4, v232, v152
	v_mul_f32_e32 v5, v5, v228
	v_mul_f32_e32 v5, v5, v223
	v_fma_f32 v5, v5, v232, v153
	v_mul_f32_e32 v6, v6, v228
	v_mul_f32_e32 v6, v6, v224
	v_fma_f32 v6, v6, v232, v154
	v_mul_f32_e32 v7, v7, v228
	v_mul_f32_e32 v7, v7, v225
	v_fma_f32 v7, v7, v232, v155
	v_mul_f32_e32 v0, v0, v229
	v_mul_f32_e32 v0, v0, v222
	v_fma_f32 v0, v0, v233, v156
	v_mul_f32_e32 v1, v1, v229
	v_mul_f32_e32 v1, v1, v223
	v_fma_f32 v1, v1, v233, v157
	v_mul_f32_e32 v2, v2, v229
	v_mul_f32_e32 v2, v2, v224
	v_fma_f32 v2, v2, v233, v158
	v_mul_f32_e32 v3, v3, v229
	v_mul_f32_e32 v3, v3, v225
	v_fma_f32 v3, v3, v233, v159
	global_store_dword v176, v36, s[36:37]
	global_store_dword v177, v37, s[36:37]
	global_store_dword v178, v38, s[36:37]
	global_store_dword v179, v39, s[36:37]
	global_store_dword v176, v28, s[36:37] offset:64
	global_store_dword v177, v29, s[36:37] offset:64
	global_store_dword v178, v30, s[36:37] offset:64
	global_store_dword v179, v31, s[36:37] offset:64
	global_store_dword v176, v4, s[36:37] offset:512
	global_store_dword v177, v5, s[36:37] offset:512
	global_store_dword v178, v6, s[36:37] offset:512
	global_store_dword v179, v7, s[36:37] offset:512
	global_store_dword v176, v0, s[36:37] offset:576
	global_store_dword v177, v1, s[36:37] offset:576
	global_store_dword v178, v2, s[36:37] offset:576
	global_store_dword v179, v3, s[36:37] offset:576
	v_readlane_b32 s0, v254, 1
	s_add_i32 s44, s44, s0
	s_barrier
	v_readlane_b32 s1, v254, 2
	s_cmp_ge_i32 s44, s46
	s_cbranch_scc1 .LBB0_1172

.Lgo_sk_dec:
	s_cmpk_eq_u32 s16, 0x44
	s_cbranch_scc0 .Lgo_fz_dec
	v_readlane_b32 s0, v254, 1
	s_cmpk_eq_u32 s0, 0x100
	s_cbranch_scc0 .Lgo_fz_dec
	s_mov_b32 s0, s2
	s_cmpk_lt_u32 s2, 0x200
	s_cbranch_scc0 .Lgo_fz_w68
	s_mov_b32 s3, 3
	s_and_b32 s0, s2, 7
	s_lshr_b32 s1, s2, 3
	s_lshr_b32 s34, s1, 5
	s_and_b32 s1, s1, 31
	s_lshl_b32 s34, s34, 5
	s_lshl_b32 s0, s0, 2
	s_add_u32 s34, s34, s0
	s_and_b32 s0, s1, 3
	s_add_u32 s34, s34, s0
	s_lshr_b32 s1, s1, 2
	s_lshl_b32 s1, s1, 3
	s_and_b32 s0, s34, 7
	s_or_b32 s1, s1, s0
	s_lshr_b32 s0, s34, 3
	s_lshl_b32 s0, s0, 6
	s_or_b32 s0, s0, s1
.Lgo_fz_w68:
	s_mul_i32 s1, s0, 241
	s_lshr_b32 s1, s1, 14
	s_mul_i32 s34, s1, 68
	s_sub_u32 s0, s0, s34
	s_lshl_b32 s0, s0, 3
	s_add_u32 s2, s0, s1

.LBB0_1277:
.Lpost_entry:
	v_readlane_b32 s40, v255, 0
	v_readlane_b32 s9, v254, 1
	s_cmpk_eq_u32 s9, 0x100
	s_cselect_b32 s44, 1, 0
	s_cmp_eq_u32 s40, 1
	s_cbranch_scc0 .Lpost_go
	s_cmp_eq_u32 s44, 1
	s_cbranch_scc1 .Lpost_done

.Lpost_row:
	s_lshl_b32 s10, s16, 13
	s_add_u32 s42, s38, s10
	s_addc_u32 s43, s39, 0
	s_lshr_b32 s8, s16, 12
	s_min_u32 s8, s8, 4
	s_add_u32 s11, s16, 0xffffc000
	s_lshl_b32 s11, s11, 13
	s_cmp_lt_u32 s16, 0x4000
	s_cbranch_scc0 .Lpost_ctxrow
	s_add_u32 s20, s14, s10
	s_addc_u32 s21, s15, 0
	s_add_u32 s0, s22, s10
	s_addc_u32 s1, s23, 0
	s_cmp_eq_u32 s40, 0
	s_cselect_b32 s0, s0, s20
	s_cselect_b32 s1, s1, s21
	s_cmp_eq_u32 s44, 1
	s_cbranch_scc1 .Lpost_fz
	s_branch .Lpost_ptrs

.Lpost_pre:
	s_add_u32 s9, s8, 5
	s_mul_i32 s9, s9, 0x6000
	s_add_u32 s12, s26, s9
	s_addc_u32 s13, s27, 0
	s_add_u32 s0, s12, 0x2000
	s_addc_u32 s1, s13, 0
	global_load_dwordx4 v[32:35], v226, s[12:13]
	global_load_dwordx4 v[36:39], v226, s[12:13] offset:1024
	global_load_dwordx4 v[40:43], v226, s[12:13] offset:2048
	global_load_dwordx4 v[44:47], v226, s[12:13] offset:3072
	global_load_dwordx4 v[48:51], v227, s[12:13]
	global_load_dwordx4 v[52:55], v227, s[12:13] offset:1024
	global_load_dwordx4 v[56:59], v227, s[12:13] offset:2048
	global_load_dwordx4 v[60:63], v227, s[12:13] offset:3072
	global_load_dwordx4 v[64:67], v226, s[0:1]
	global_load_dwordx4 v[68:71], v226, s[0:1] offset:1024
	global_load_dwordx4 v[72:75], v226, s[0:1] offset:2048
	global_load_dwordx4 v[76:79], v226, s[0:1] offset:3072
	global_load_dwordx4 v[80:83], v227, s[0:1]
	global_load_dwordx4 v[84:87], v227, s[0:1] offset:1024
	global_load_dwordx4 v[88:91], v227, s[0:1] offset:2048
	global_load_dwordx4 v[92:95], v227, s[0:1] offset:3072
	s_lshl_b32 s10, s16, 12
	s_add_u32 s10, s36, s10
	s_addc_u32 s11, s37, 0
	v_mul_f32_e32 v132, v0, v0
	v_mul_f32_e32 v133, v1, v1
	v_mul_f32_e32 v134, v2, v2
	v_mul_f32_e32 v135, v3, v3
	v_add_f32_e32 v128, v132, v133
	v_add_f32_e32 v128, v128, v134
	v_add_f32_e32 v128, v128, v135
	v_mul_f32_e32 v132, v4, v4
	v_mul_f32_e32 v133, v5, v5
	v_mul_f32_e32 v134, v6, v6
	v_mul_f32_e32 v135, v7, v7
	v_add_f32_e32 v129, v132, v133
	v_add_f32_e32 v129, v129, v134
	v_add_f32_e32 v129, v129, v135
	v_mul_f32_e32 v132, v8, v8
	v_mul_f32_e32 v133, v9, v9
	v_mul_f32_e32 v134, v10, v10
	v_mul_f32_e32 v135, v11, v11
	v_add_f32_e32 v130, v132, v133
	v_add_f32_e32 v130, v130, v134
	v_add_f32_e32 v130, v130, v135
	v_mul_f32_e32 v132, v12, v12
	v_mul_f32_e32 v133, v13, v13
	v_mul_f32_e32 v134, v14, v14
	v_mul_f32_e32 v135, v15, v15
	v_add_f32_e32 v131, v132, v133
	v_add_f32_e32 v131, v131, v134
	v_add_f32_e32 v131, v131, v135
	v_add_f32_e32 v229, v128, v129
	v_add_f32_e32 v229, v229, v130
	v_add_f32_e32 v229, v229, v131
	v_mul_f32_e32 v128, v17, v17
	v_fmac_f32_e32 v128, v16, v16
	v_fmac_f32_e32 v128, v18, v18
	v_fmac_f32_e32 v128, v19, v19
	v_mul_f32_e32 v129, v21, v21
	v_fmac_f32_e32 v129, v20, v20
	v_fmac_f32_e32 v129, v22, v22
	v_fmac_f32_e32 v129, v23, v23
	v_mul_f32_e32 v130, v25, v25
	v_fmac_f32_e32 v130, v24, v24
	v_fmac_f32_e32 v130, v26, v26
	v_fmac_f32_e32 v130, v27, v27
	v_mul_f32_e32 v131, v29, v29
	v_fmac_f32_e32 v131, v28, v28
	v_fmac_f32_e32 v131, v30, v30
	v_fmac_f32_e32 v131, v31, v31
	v_add_f32_e32 v229, v229, v128
	v_add_f32_e32 v229, v229, v129
	v_add_f32_e32 v229, v229, v130
	v_add_f32_e32 v229, v229, v131
	v_mov_b32_e32 v231, v229
	s_nop 1
	v_permlane32_swap_b32_e32 v229, v231
	s_nop 0
	v_add_f32_e32 v229, v229, v231
	v_mov_b32_e32 v231, v229
	s_nop 1
	v_permlane16_swap_b32_e32 v229, v231
	s_nop 0
	v_add_f32_e32 v229, v229, v231
	s_nop 1
	v_add_f32_dpp v229, v229, v229 row_ror:8 row_mask:0xf bank_mask:0xf
	s_nop 1
	v_add_f32_dpp v229, v229, v229 row_ror:4 row_mask:0xf bank_mask:0xf
	s_nop 1
	v_add_f32_dpp v229, v229, v229 row_ror:2 row_mask:0xf bank_mask:0xf
	s_nop 1
	v_add_f32_dpp v229, v229, v229 row_ror:1 row_mask:0xf bank_mask:0xf
	v_fmamk_f32 v229, v229, 0x3a000000, v166
	v_mul_f32_e32 v231, 0x4b800000, v229
	v_cmp_gt_f32_e32 vcc, s58, v229
	s_nop 1
	v_cndmask_b32_e32 v229, v229, v231, vcc
	v_rsq_f32_e32 v230, v229
	s_nop 0
	v_mul_f32_e32 v231, 0x45800000, v230
	v_cndmask_b32_e32 v230, v230, v231, vcc
	s_waitcnt vmcnt(0)
	v_mul_f32_e32 v0, v0, v230
	v_mul_f32_e32 v0, v194, v0
	v_add_f32_e32 v64, 1.0, v64
	v_fma_f32 v0, v64, v0, v32
	v_mul_f32_e32 v1, v1, v230
	v_mul_f32_e32 v1, v195, v1
	v_add_f32_e32 v65, 1.0, v65
	v_fma_f32 v1, v65, v1, v33
	v_mul_f32_e32 v2, v2, v230
	v_mul_f32_e32 v2, v196, v2
	v_add_f32_e32 v66, 1.0, v66
	v_fma_f32 v2, v66, v2, v34
	v_mul_f32_e32 v3, v3, v230
	v_mul_f32_e32 v3, v197, v3
	v_add_f32_e32 v67, 1.0, v67
	v_fma_f32 v3, v67, v3, v35
	v_cvt_pk_bf16_f32 v0, v0, v1
	v_cvt_pk_bf16_f32 v1, v2, v3
	global_store_dwordx2 v228, v[0:1], s[10:11]
	v_mul_f32_e32 v4, v4, v230
	v_mul_f32_e32 v4, v198, v4
	v_add_f32_e32 v68, 1.0, v68
	v_fma_f32 v4, v68, v4, v36
	v_mul_f32_e32 v5, v5, v230
	v_mul_f32_e32 v5, v199, v5
	v_add_f32_e32 v69, 1.0, v69
	v_fma_f32 v5, v69, v5, v37
	v_mul_f32_e32 v6, v6, v230
	v_mul_f32_e32 v6, v200, v6
	v_add_f32_e32 v70, 1.0, v70
	v_fma_f32 v6, v70, v6, v38
	v_mul_f32_e32 v7, v7, v230
	v_mul_f32_e32 v7, v201, v7
	v_add_f32_e32 v71, 1.0, v71
	v_fma_f32 v7, v71, v7, v39
	v_cvt_pk_bf16_f32 v4, v4, v5
	v_cvt_pk_bf16_f32 v5, v6, v7
	global_store_dwordx2 v228, v[4:5], s[10:11] offset:512
	v_mul_f32_e32 v8, v8, v230
	v_mul_f32_e32 v8, v202, v8
	v_add_f32_e32 v72, 1.0, v72
	v_fma_f32 v8, v72, v8, v40
	v_mul_f32_e32 v9, v9, v230
	v_mul_f32_e32 v9, v203, v9
	v_add_f32_e32 v73, 1.0, v73
	v_fma_f32 v9, v73, v9, v41
	v_mul_f32_e32 v10, v10, v230
	v_mul_f32_e32 v10, v204, v10
	v_add_f32_e32 v74, 1.0, v74
	v_fma_f32 v10, v74, v10, v42
	v_mul_f32_e32 v11, v11, v230
	v_mul_f32_e32 v11, v205, v11
	v_add_f32_e32 v75, 1.0, v75
	v_fma_f32 v11, v75, v11, v43
	v_cvt_pk_bf16_f32 v8, v8, v9
	v_cvt_pk_bf16_f32 v9, v10, v11
	global_store_dwordx2 v228, v[8:9], s[10:11] offset:1024
	v_mul_f32_e32 v12, v12, v230
	v_mul_f32_e32 v12, v206, v12
	v_add_f32_e32 v76, 1.0, v76
	v_fma_f32 v12, v76, v12, v44
	v_mul_f32_e32 v13, v13, v230
	v_mul_f32_e32 v13, v207, v13
	v_add_f32_e32 v77, 1.0, v77
	v_fma_f32 v13, v77, v13, v45
	v_mul_f32_e32 v14, v14, v230
	v_mul_f32_e32 v14, v208, v14
	v_add_f32_e32 v78, 1.0, v78
	v_fma_f32 v14, v78, v14, v46
	v_mul_f32_e32 v15, v15, v230
	v_mul_f32_e32 v15, v209, v15
	v_add_f32_e32 v79, 1.0, v79
	v_fma_f32 v15, v79, v15, v47
	v_cvt_pk_bf16_f32 v12, v12, v13
	v_cvt_pk_bf16_f32 v13, v14, v15
	global_store_dwordx2 v228, v[12:13], s[10:11] offset:1536
	v_mul_f32_e32 v16, v16, v230
	v_mul_f32_e32 v16, v210, v16
	v_add_f32_e32 v80, 1.0, v80
	v_fma_f32 v16, v80, v16, v48
	v_mul_f32_e32 v17, v17, v230
	v_mul_f32_e32 v17, v211, v17
	v_add_f32_e32 v81, 1.0, v81
	v_fma_f32 v17, v81, v17, v49
	v_mul_f32_e32 v18, v18, v230
	v_mul_f32_e32 v18, v212, v18
	v_add_f32_e32 v82, 1.0, v82
	v_fma_f32 v18, v82, v18, v50
	v_mul_f32_e32 v19, v19, v230
	v_mul_f32_e32 v19, v213, v19
	v_add_f32_e32 v83, 1.0, v83
	v_fma_f32 v19, v83, v19, v51
	v_cvt_pk_bf16_f32 v16, v16, v17
	v_cvt_pk_bf16_f32 v17, v18, v19
	global_store_dwordx2 v228, v[16:17], s[10:11] offset:2048
	v_mul_f32_e32 v20, v20, v230
	v_mul_f32_e32 v20, v214, v20
	v_add_f32_e32 v84, 1.0, v84
	v_fma_f32 v20, v84, v20, v52
	v_mul_f32_e32 v21, v21, v230
	v_mul_f32_e32 v21, v215, v21
	v_add_f32_e32 v85, 1.0, v85
	v_fma_f32 v21, v85, v21, v53
	v_mul_f32_e32 v22, v22, v230
	v_mul_f32_e32 v22, v216, v22
	v_add_f32_e32 v86, 1.0, v86
	v_fma_f32 v22, v86, v22, v54
	v_mul_f32_e32 v23, v23, v230
	v_mul_f32_e32 v23, v217, v23
	v_add_f32_e32 v87, 1.0, v87
	v_fma_f32 v23, v87, v23, v55
	v_cvt_pk_bf16_f32 v20, v20, v21
	v_cvt_pk_bf16_f32 v21, v22, v23
	global_store_dwordx2 v228, v[20:21], s[10:11] offset:2560
	v_mul_f32_e32 v24, v24, v230
	v_mul_f32_e32 v24, v218, v24
	v_add_f32_e32 v88, 1.0, v88
	v_fma_f32 v24, v88, v24, v56
	v_mul_f32_e32 v25, v25, v230
	v_mul_f32_e32 v25, v219, v25
	v_add_f32_e32 v89, 1.0, v89
	v_fma_f32 v25, v89, v25, v57
	v_mul_f32_e32 v26, v26, v230
	v_mul_f32_e32 v26, v220, v26
	v_add_f32_e32 v90, 1.0, v90
	v_fma_f32 v26, v90, v26, v58
	v_mul_f32_e32 v27, v27, v230
	v_mul_f32_e32 v27, v221, v27
	v_add_f32_e32 v91, 1.0, v91
	v_fma_f32 v27, v91, v27, v59
	v_cvt_pk_bf16_f32 v24, v24, v25
	v_cvt_pk_bf16_f32 v25, v26, v27
	global_store_dwordx2 v228, v[24:25], s[10:11] offset:3072
	v_mul_f32_e32 v28, v28, v230
	v_mul_f32_e32 v28, v222, v28
	v_add_f32_e32 v92, 1.0, v92
	v_fma_f32 v28, v92, v28, v60
	v_mul_f32_e32 v29, v29, v230
	v_mul_f32_e32 v29, v223, v29
	v_add_f32_e32 v93, 1.0, v93
	v_fma_f32 v29, v93, v29, v61
	v_mul_f32_e32 v30, v30, v230
	v_mul_f32_e32 v30, v224, v30
	v_add_f32_e32 v94, 1.0, v94
	v_fma_f32 v30, v94, v30, v62
	v_mul_f32_e32 v31, v31, v230
	v_mul_f32_e32 v31, v225, v31
	v_add_f32_e32 v95, 1.0, v95
	v_fma_f32 v31, v95, v31, v63
	v_cvt_pk_bf16_f32 v28, v28, v29
	v_cvt_pk_bf16_f32 v29, v30, v31
	global_store_dwordx2 v228, v[28:29], s[10:11] offset:3584

.Lpost_fz:
	global_load_dwordx4 v[0:3], v226, s[20:21]
	global_load_dwordx4 v[4:7], v226, s[20:21] offset:1024
	global_load_dwordx4 v[8:11], v226, s[20:21] offset:2048
	global_load_dwordx4 v[12:15], v226, s[20:21] offset:3072
	global_load_dwordx4 v[16:19], v227, s[20:21]
	global_load_dwordx4 v[20:23], v227, s[20:21] offset:1024
	global_load_dwordx4 v[24:27], v227, s[20:21] offset:2048
	global_load_dwordx4 v[28:31], v227, s[20:21] offset:3072
	s_waitcnt vmcnt(0)
	s_branch .Lpost_pre
